# up-GEMM loop: one A-half DMA piece moved from the 6-piece load section to the following 2-piece section (vmcnt 7)
# speedup vs baseline: 1.0026x; 1.0002x over previous
; #define PG8_STAGE(bufoff, gbase, voff) do { _Pragma("unroll") for (int _i = 0; _i < 2; ++_i) \
;         __builtin_amdgcn_global_load_lds((const unsigned*)((const char*)(gbase) + (voff)[_i]), (LAS unsigned*)(lds + (bufoff) + ldsw + _i * 8192), 16, 0, 0); } while (0)
; #define PG8_LDA(dst, b, h) do { _Pragma("unroll") for (int m = 0; m < NM; ++m) _Pragma("unroll") for (int k = 0; k < 2; ++k) dst[m][k] = *(const LAS bf16x8*)(lds + PG8_SA(b, h) + aoff + m * 2048 + k * 1024); } while (0)
; #define PG8_LDB(dst, b, h) do { _Pragma("unroll") for (int n = 0; n < 2; ++n) _Pragma("unroll") for (int k = 0; k < 2; ++k) dst[n][k] = *(const LAS bf16x8*)(lds + PG8_SB(b, h) + boff + n * 2048 + k * 1024); } while (0)
; #define PG8_MMA(ai, bj, At, Bt) do { __builtin_amdgcn_s_setprio(1); _Pragma("unroll") for (int m = 0; m < NM; ++m) _Pragma("unroll") for (int n = 0; n < 2; ++n) _Pragma("unroll") for (int k = 0; k < 2; ++k) \
;         acc[ai][bj][m][n] = __builtin_amdgcn_mfma_f32_16x16x32_bf16(Bt[n][k], At[m][k], acc[ai][bj][m][n], 0, 0, 0); __builtin_amdgcn_s_setprio(0); } while (0)
; #define PG8_WAIT_V(n) asm volatile("s_waitcnt vmcnt(" #n ")" ::: "memory")
; #define PG8_WAIT_L(n) asm volatile("s_waitcnt lgkmcnt(" #n ")" ::: "memory")
; #define PG8_BAR __builtin_amdgcn_s_barrier()
; #define PG8_SCHED __builtin_amdgcn_sched_barrier(0)
;     ...
;         for (int t = 0; t < nt; t += 2) {
;             const bool last = (t == nt - 2);
;             const char* a1 = cA + (size_t)(t + 1) * kstep;
;             const char* a2 = last ? nA : cA + (size_t)(t + 2) * kstep; const char* b2 = last ? nB : cB + (size_t)(t + 2) * kstep;
;             const char* a3 = a2 + kstep; const char* b3 = b2 + kstep;
;             if constexpr (SP2) {
;             PG8_LDB(B0, 0, 0); PG8_LDB(B1, 0, 1); PG8_SCHED; PG8_LDA(At, 0, 0); PG8_STAGE(PG8_SA(1, 1), a1 + hstepA, voffA);
;             PG8_WAIT_V(8); PG8_WAIT_L(0); PG8_BAR; PG8_MMA(0, 0, At, B0); PG8_MMA(0, 1, At, B1); PG8_BAR; PG8_SCHED;
;             PG8_LDA(At, 0, 1); PG8_STAGE(PG8_SB(0, 0), b2, voffB); PG8_STAGE(PG8_SB(0, 1), b2 + hstepB, voffB); PG8_STAGE(PG8_SA(0, 0), a2, voffA);
;             PG8_WAIT_V(8); PG8_WAIT_L(0); PG8_BAR; PG8_MMA(1, 0, At, B0); PG8_MMA(1, 1, At, B1); PG8_BAR; PG8_SCHED;
.LBB0_1783:
	v_add_u32_e32 v0, s64, v208
	ds_read_b128 v[130:133], v0
	ds_read_b128 v[134:137], v0 offset:1024
	ds_read_b128 v[138:141], v0 offset:2048
	ds_read_b128 v[142:145], v0 offset:3072
	v_add_u32_e32 v0, s70, v208
	ds_read_b128 v[146:149], v0
	ds_read_b128 v[150:153], v0 offset:1024
	ds_read_b128 v[154:157], v0 offset:2048
	ds_read_b128 v[158:161], v0 offset:3072
	s_add_u32 s14, s12, 0xfff80080
	s_addc_u32 s15, s13, -1
	s_cmp_eq_u32 vcc_lo, 28
	s_cselect_b32 s47, s2, s15
	s_cselect_b32 s46, s3, s14
	s_cselect_b32 s15, s9, s41
	s_cselect_b32 s14, s11, s37
	s_add_i32 m0, s73, 0xc000
	ds_read_b128 v[162:165], v209
	ds_read_b128 v[166:169], v209 offset:1024
	ds_read_b128 v[170:173], v209 offset:2048
	ds_read_b128 v[174:177], v209 offset:3072
	ds_read_b128 v[190:193], v209 offset:4096
	ds_read_b128 v[194:197], v209 offset:5120
	ds_read_b128 v[198:201], v209 offset:6144
	ds_read_b128 v[202:205], v209 offset:7168
	global_load_lds_dwordx4 v186, s[12:13]
	s_add_i32 m0, s73, 0xe000
	s_nop 0
	global_load_lds_dwordx4 v188, s[12:13]
	s_waitcnt vmcnt(8)
	s_waitcnt lgkmcnt(0)
	s_barrier
	s_setprio 1
	s_waitcnt lgkmcnt(0)
	v_mfma_f32_16x16x32_bf16 v[126:129], v[130:133], v[162:165], v[126:129]
	v_mfma_f32_16x16x32_bf16 v[94:97], v[138:141], v[162:165], v[94:97]
	v_mfma_f32_16x16x32_bf16 v[110:113], v[130:133], v[170:173], v[110:113]
	v_mfma_f32_16x16x32_bf16 v[70:73], v[138:141], v[170:173], v[70:73]
	v_mfma_f32_16x16x32_bf16 v[106:109], v[130:133], v[190:193], v[106:109]
	v_mfma_f32_16x16x32_bf16 v[66:69], v[138:141], v[190:193], v[66:69]
	v_mfma_f32_16x16x32_bf16 v[118:121], v[130:133], v[198:201], v[118:121]
	v_mfma_f32_16x16x32_bf16 v[86:89], v[138:141], v[198:201], v[86:89]
	v_mfma_f32_16x16x32_bf16 v[126:129], v[134:137], v[166:169], v[126:129]
	v_mfma_f32_16x16x32_bf16 v[94:97], v[142:145], v[166:169], v[94:97]
	v_mfma_f32_16x16x32_bf16 v[110:113], v[134:137], v[174:177], v[110:113]
	v_mfma_f32_16x16x32_bf16 v[70:73], v[142:145], v[174:177], v[70:73]
	v_mfma_f32_16x16x32_bf16 v[106:109], v[134:137], v[194:197], v[106:109]
	v_mfma_f32_16x16x32_bf16 v[66:69], v[142:145], v[194:197], v[66:69]
	v_mfma_f32_16x16x32_bf16 v[118:121], v[134:137], v[202:205], v[118:121]
	v_mfma_f32_16x16x32_bf16 v[86:89], v[142:145], v[202:205], v[86:89]
	s_setprio 0
	s_setprio 1
	v_mfma_f32_16x16x32_bf16 v[122:125], v[146:149], v[162:165], v[122:125]
	v_mfma_f32_16x16x32_bf16 v[90:93], v[154:157], v[162:165], v[90:93]
	v_mfma_f32_16x16x32_bf16 v[102:105], v[146:149], v[170:173], v[102:105]
	v_mfma_f32_16x16x32_bf16 v[62:65], v[154:157], v[170:173], v[62:65]
	v_mfma_f32_16x16x32_bf16 v[98:101], v[146:149], v[190:193], v[98:101]
	v_mfma_f32_16x16x32_bf16 v[58:61], v[154:157], v[190:193], v[58:61]
	v_mfma_f32_16x16x32_bf16 v[114:117], v[146:149], v[198:201], v[114:117]
	v_mfma_f32_16x16x32_bf16 v[82:85], v[154:157], v[198:201], v[82:85]
	v_mfma_f32_16x16x32_bf16 v[122:125], v[150:153], v[166:169], v[122:125]
	v_mfma_f32_16x16x32_bf16 v[90:93], v[158:161], v[166:169], v[90:93]
	v_mfma_f32_16x16x32_bf16 v[102:105], v[150:153], v[174:177], v[102:105]
	v_mfma_f32_16x16x32_bf16 v[62:65], v[158:161], v[174:177], v[62:65]
	v_mfma_f32_16x16x32_bf16 v[98:101], v[150:153], v[194:197], v[98:101]
	v_mfma_f32_16x16x32_bf16 v[58:61], v[158:161], v[194:197], v[58:61]
	v_mfma_f32_16x16x32_bf16 v[114:117], v[150:153], v[202:205], v[114:117]
	v_mfma_f32_16x16x32_bf16 v[82:85], v[158:161], v[202:205], v[82:85]
	s_setprio 0
	s_barrier
	s_mov_b32 m0, s68
	s_add_u32 s22, s14, 0x80000
	ds_read_b128 v[162:165], v209 offset:16384
	ds_read_b128 v[166:169], v209 offset:17408
	ds_read_b128 v[170:173], v209 offset:18432
	ds_read_b128 v[174:177], v209 offset:19456
	ds_read_b128 v[190:193], v209 offset:20480
	ds_read_b128 v[194:197], v209 offset:21504
	ds_read_b128 v[198:201], v209 offset:22528
	ds_read_b128 v[202:205], v209 offset:23552
	global_load_lds_dwordx4 v180, s[14:15]
	s_mov_b32 m0, s69
	s_addc_u32 s23, s15, 0
	global_load_lds_dwordx4 v184, s[14:15]
	s_mov_b32 m0, s71
	s_nop 0
	global_load_lds_dwordx4 v180, s[22:23]
	s_mov_b32 m0, s72
	s_nop 0
	global_load_lds_dwordx4 v184, s[22:23]
	s_mov_b32 m0, s73
	s_nop 0
	global_load_lds_dwordx4 v178, s[46:47]
	s_waitcnt vmcnt(7)
	s_waitcnt lgkmcnt(0)
	s_barrier
	s_setprio 1
	s_waitcnt lgkmcnt(0)
	v_mfma_f32_16x16x32_bf16 v[46:49], v[130:133], v[162:165], v[46:49]
	v_mfma_f32_16x16x32_bf16 v[22:25], v[138:141], v[162:165], v[22:25]
	v_mfma_f32_16x16x32_bf16 v[42:45], v[130:133], v[170:173], v[42:45]
	v_mfma_f32_16x16x32_bf16 v[18:21], v[138:141], v[170:173], v[18:21]
	v_mfma_f32_16x16x32_bf16 v[38:41], v[130:133], v[190:193], v[38:41]
	v_mfma_f32_16x16x32_bf16 v[14:17], v[138:141], v[190:193], v[14:17]
	v_mfma_f32_16x16x32_bf16 v[78:81], v[130:133], v[198:201], v[78:81]
	v_mfma_f32_16x16x32_bf16 v[54:57], v[138:141], v[198:201], v[54:57]
	v_mfma_f32_16x16x32_bf16 v[46:49], v[134:137], v[166:169], v[46:49]
	v_mfma_f32_16x16x32_bf16 v[22:25], v[142:145], v[166:169], v[22:25]
	v_mfma_f32_16x16x32_bf16 v[42:45], v[134:137], v[174:177], v[42:45]
	v_mfma_f32_16x16x32_bf16 v[18:21], v[142:145], v[174:177], v[18:21]
	v_mfma_f32_16x16x32_bf16 v[38:41], v[134:137], v[194:197], v[38:41]
	v_mfma_f32_16x16x32_bf16 v[14:17], v[142:145], v[194:197], v[14:17]
	v_mfma_f32_16x16x32_bf16 v[78:81], v[134:137], v[202:205], v[78:81]
	v_mfma_f32_16x16x32_bf16 v[54:57], v[142:145], v[202:205], v[54:57]
	s_setprio 0
	s_setprio 1
	v_mfma_f32_16x16x32_bf16 v[34:37], v[146:149], v[162:165], v[34:37]
	v_mfma_f32_16x16x32_bf16 v[10:13], v[154:157], v[162:165], v[10:13]
	v_mfma_f32_16x16x32_bf16 v[30:33], v[146:149], v[170:173], v[30:33]
	v_mfma_f32_16x16x32_bf16 v[6:9], v[154:157], v[170:173], v[6:9]
	v_mfma_f32_16x16x32_bf16 v[26:29], v[146:149], v[190:193], v[26:29]
	v_mfma_f32_16x16x32_bf16 v[2:5], v[154:157], v[190:193], v[2:5]
	v_mfma_f32_16x16x32_bf16 v[74:77], v[146:149], v[198:201], v[74:77]
	v_mfma_f32_16x16x32_bf16 v[50:53], v[154:157], v[198:201], v[50:53]
	v_mfma_f32_16x16x32_bf16 v[34:37], v[150:153], v[166:169], v[34:37]
	v_mfma_f32_16x16x32_bf16 v[10:13], v[158:161], v[166:169], v[10:13]
	v_mfma_f32_16x16x32_bf16 v[30:33], v[150:153], v[174:177], v[30:33]
	v_mfma_f32_16x16x32_bf16 v[6:9], v[158:161], v[174:177], v[6:9]
	v_mfma_f32_16x16x32_bf16 v[26:29], v[150:153], v[194:197], v[26:29]
	v_mfma_f32_16x16x32_bf16 v[2:5], v[158:161], v[194:197], v[2:5]
	v_mfma_f32_16x16x32_bf16 v[74:77], v[150:153], v[202:205], v[74:77]
	v_mfma_f32_16x16x32_bf16 v[50:53], v[158:161], v[202:205], v[50:53]
	s_setprio 0
	s_barrier
; #define PG8_STAGE(bufoff, gbase, voff) do { _Pragma("unroll") for (int _i = 0; _i < 2; ++_i) \
;         __builtin_amdgcn_global_load_lds((const unsigned*)((const char*)(gbase) + (voff)[_i]), (LAS unsigned*)(lds + (bufoff) + ldsw + _i * 8192), 16, 0, 0); } while (0)
; #define PG8_LDA(dst, b, h) do { _Pragma("unroll") for (int m = 0; m < NM; ++m) _Pragma("unroll") for (int k = 0; k < 2; ++k) dst[m][k] = *(const LAS bf16x8*)(lds + PG8_SA(b, h) + aoff + m * 2048 + k * 1024); } while (0)
; #define PG8_LDB(dst, b, h) do { _Pragma("unroll") for (int n = 0; n < 2; ++n) _Pragma("unroll") for (int k = 0; k < 2; ++k) dst[n][k] = *(const LAS bf16x8*)(lds + PG8_SB(b, h) + boff + n * 2048 + k * 1024); } while (0)
; #define PG8_MMA(ai, bj, At, Bt) do { __builtin_amdgcn_s_setprio(1); _Pragma("unroll") for (int m = 0; m < NM; ++m) _Pragma("unroll") for (int n = 0; n < 2; ++n) _Pragma("unroll") for (int k = 0; k < 2; ++k) \
;         acc[ai][bj][m][n] = __builtin_amdgcn_mfma_f32_16x16x32_bf16(Bt[n][k], At[m][k], acc[ai][bj][m][n], 0, 0, 0); __builtin_amdgcn_s_setprio(0); } while (0)
; #define PG8_WAIT_V(n) asm volatile("s_waitcnt vmcnt(" #n ")" ::: "memory")
; #define PG8_WAIT_L(n) asm volatile("s_waitcnt lgkmcnt(" #n ")" ::: "memory")
; #define PG8_BAR __builtin_amdgcn_s_barrier()
; #define PG8_SCHED __builtin_amdgcn_sched_barrier(0)
;     ...
;             PG8_LDB(B0, 1, 0); PG8_LDB(B1, 1, 1); PG8_SCHED; PG8_LDA(At, 1, 0); PG8_STAGE(PG8_SA(0, 1), a2 + hstepA, voffA);
;             PG8_WAIT_V(8); PG8_WAIT_L(0); PG8_BAR; PG8_MMA(0, 0, At, B0); PG8_MMA(0, 1, At, B1); PG8_BAR; PG8_SCHED;
;             PG8_LDA(At, 1, 1); PG8_STAGE(PG8_SB(1, 0), b3, voffB); PG8_STAGE(PG8_SB(1, 1), b3 + hstepB, voffB); PG8_STAGE(PG8_SA(1, 0), a3, voffA);
;             PG8_WAIT_V(8); PG8_WAIT_L(0); PG8_BAR; PG8_MMA(1, 0, At, B0); PG8_MMA(1, 1, At, B1); PG8_BAR; PG8_SCHED;
	v_add_u32_e32 v0, s94, v208
	ds_read_b128 v[130:133], v0
	ds_read_b128 v[134:137], v0 offset:1024
	ds_read_b128 v[138:141], v0 offset:2048
	ds_read_b128 v[142:145], v0 offset:3072
	v_add_u32_e32 v0, s62, v208
	ds_read_b128 v[146:149], v0
	ds_read_b128 v[150:153], v0 offset:1024
	ds_read_b128 v[154:157], v0 offset:2048
	ds_read_b128 v[158:161], v0 offset:3072
	s_add_u32 s22, s46, 0x80000
	s_addc_u32 s23, s47, 0
	s_mov_b32 m0, s74
	s_nop 0
	global_load_lds_dwordx4 v182, s[46:47]
	s_mov_b32 m0, s75
	ds_read_b128 v[162:165], v209 offset:32768
	ds_read_b128 v[166:169], v209 offset:33792
	ds_read_b128 v[170:173], v209 offset:34816
	ds_read_b128 v[174:177], v209 offset:35840
	ds_read_b128 v[190:193], v209 offset:36864
	ds_read_b128 v[194:197], v209 offset:37888
	ds_read_b128 v[198:201], v209 offset:38912
	ds_read_b128 v[202:205], v209 offset:39936
	global_load_lds_dwordx4 v178, s[22:23]
	s_mov_b32 m0, s80
	s_nop 0
	global_load_lds_dwordx4 v182, s[22:23]
	s_waitcnt vmcnt(8)
	s_waitcnt lgkmcnt(0)
	s_barrier
	s_setprio 1
	s_waitcnt lgkmcnt(0)
	v_mfma_f32_16x16x32_bf16 v[126:129], v[130:133], v[162:165], v[126:129]
	v_mfma_f32_16x16x32_bf16 v[94:97], v[138:141], v[162:165], v[94:97]
	v_mfma_f32_16x16x32_bf16 v[110:113], v[130:133], v[170:173], v[110:113]
	v_mfma_f32_16x16x32_bf16 v[70:73], v[138:141], v[170:173], v[70:73]
	v_mfma_f32_16x16x32_bf16 v[106:109], v[130:133], v[190:193], v[106:109]
	v_mfma_f32_16x16x32_bf16 v[66:69], v[138:141], v[190:193], v[66:69]
	v_mfma_f32_16x16x32_bf16 v[118:121], v[130:133], v[198:201], v[118:121]
	v_mfma_f32_16x16x32_bf16 v[86:89], v[138:141], v[198:201], v[86:89]
	v_mfma_f32_16x16x32_bf16 v[126:129], v[134:137], v[166:169], v[126:129]
	v_mfma_f32_16x16x32_bf16 v[94:97], v[142:145], v[166:169], v[94:97]
	v_mfma_f32_16x16x32_bf16 v[110:113], v[134:137], v[174:177], v[110:113]
	v_mfma_f32_16x16x32_bf16 v[70:73], v[142:145], v[174:177], v[70:73]
	v_mfma_f32_16x16x32_bf16 v[106:109], v[134:137], v[194:197], v[106:109]
	v_mfma_f32_16x16x32_bf16 v[66:69], v[142:145], v[194:197], v[66:69]
	v_mfma_f32_16x16x32_bf16 v[118:121], v[134:137], v[202:205], v[118:121]
	v_mfma_f32_16x16x32_bf16 v[86:89], v[142:145], v[202:205], v[86:89]
	s_setprio 0
	s_setprio 1
	v_mfma_f32_16x16x32_bf16 v[122:125], v[146:149], v[162:165], v[122:125]
	v_mfma_f32_16x16x32_bf16 v[90:93], v[154:157], v[162:165], v[90:93]
	v_mfma_f32_16x16x32_bf16 v[102:105], v[146:149], v[170:173], v[102:105]
	v_mfma_f32_16x16x32_bf16 v[62:65], v[154:157], v[170:173], v[62:65]
	v_mfma_f32_16x16x32_bf16 v[98:101], v[146:149], v[190:193], v[98:101]
	v_mfma_f32_16x16x32_bf16 v[58:61], v[154:157], v[190:193], v[58:61]
	v_mfma_f32_16x16x32_bf16 v[114:117], v[146:149], v[198:201], v[114:117]
	v_mfma_f32_16x16x32_bf16 v[82:85], v[154:157], v[198:201], v[82:85]
	v_mfma_f32_16x16x32_bf16 v[122:125], v[150:153], v[166:169], v[122:125]
	v_mfma_f32_16x16x32_bf16 v[90:93], v[158:161], v[166:169], v[90:93]
	v_mfma_f32_16x16x32_bf16 v[102:105], v[150:153], v[174:177], v[102:105]
	v_mfma_f32_16x16x32_bf16 v[62:65], v[158:161], v[174:177], v[62:65]
	v_mfma_f32_16x16x32_bf16 v[98:101], v[150:153], v[194:197], v[98:101]
	v_mfma_f32_16x16x32_bf16 v[58:61], v[158:161], v[194:197], v[58:61]
	v_mfma_f32_16x16x32_bf16 v[114:117], v[150:153], v[202:205], v[114:117]
	v_mfma_f32_16x16x32_bf16 v[82:85], v[158:161], v[202:205], v[82:85]
	s_setprio 0
	s_barrier
	s_mov_b32 m0, s51
	s_add_u32 s100, s14, s66
	s_addc_u32 s101, s15, s67
	s_add_u32 s14, s14, 0x80080
	s_addc_u32 s15, s15, 0
	ds_read_b128 v[162:165], v209 offset:49152
	ds_read_b128 v[166:169], v209 offset:50176
	ds_read_b128 v[170:173], v209 offset:51200
	ds_read_b128 v[174:177], v209 offset:52224
	ds_read_b128 v[190:193], v209 offset:53248
	ds_read_b128 v[194:197], v209 offset:54272
	ds_read_b128 v[198:201], v209 offset:55296
	ds_read_b128 v[202:205], v209 offset:56320
	global_load_lds_dwordx4 v180, s[100:101]
	s_mov_b32 m0, s95
	s_nop 0
	global_load_lds_dwordx4 v184, s[100:101]
	s_add_u32 s100, s46, s66
	s_addc_u32 s101, s47, s67
	s_mov_b32 m0, s50
	s_nop 0
	global_load_lds_dwordx4 v180, s[14:15]
	s_mov_b32 m0, s49
	s_nop 0
	global_load_lds_dwordx4 v184, s[14:15]
	s_mov_b32 m0, s58
	s_nop 0
	global_load_lds_dwordx4 v178, s[100:101]
	s_mov_b32 m0, s59
	s_nop 0
	global_load_lds_dwordx4 v182, s[100:101]
	s_waitcnt vmcnt(8)
	s_waitcnt lgkmcnt(0)
	s_barrier
	s_setprio 1
	s_waitcnt lgkmcnt(0)
	v_mfma_f32_16x16x32_bf16 v[46:49], v[130:133], v[162:165], v[46:49]
	v_mfma_f32_16x16x32_bf16 v[22:25], v[138:141], v[162:165], v[22:25]
	v_mfma_f32_16x16x32_bf16 v[42:45], v[130:133], v[170:173], v[42:45]
	v_mfma_f32_16x16x32_bf16 v[18:21], v[138:141], v[170:173], v[18:21]
	v_mfma_f32_16x16x32_bf16 v[38:41], v[130:133], v[190:193], v[38:41]
	v_mfma_f32_16x16x32_bf16 v[14:17], v[138:141], v[190:193], v[14:17]
	v_mfma_f32_16x16x32_bf16 v[78:81], v[130:133], v[198:201], v[78:81]
	v_mfma_f32_16x16x32_bf16 v[54:57], v[138:141], v[198:201], v[54:57]
	v_mfma_f32_16x16x32_bf16 v[46:49], v[134:137], v[166:169], v[46:49]
	v_mfma_f32_16x16x32_bf16 v[22:25], v[142:145], v[166:169], v[22:25]
	v_mfma_f32_16x16x32_bf16 v[42:45], v[134:137], v[174:177], v[42:45]
	v_mfma_f32_16x16x32_bf16 v[18:21], v[142:145], v[174:177], v[18:21]
	v_mfma_f32_16x16x32_bf16 v[38:41], v[134:137], v[194:197], v[38:41]
	v_mfma_f32_16x16x32_bf16 v[14:17], v[142:145], v[194:197], v[14:17]
	v_mfma_f32_16x16x32_bf16 v[78:81], v[134:137], v[202:205], v[78:81]
	v_mfma_f32_16x16x32_bf16 v[54:57], v[142:145], v[202:205], v[54:57]
	s_setprio 0
	s_setprio 1
	v_mfma_f32_16x16x32_bf16 v[34:37], v[146:149], v[162:165], v[34:37]
	v_mfma_f32_16x16x32_bf16 v[10:13], v[154:157], v[162:165], v[10:13]
	v_mfma_f32_16x16x32_bf16 v[30:33], v[146:149], v[170:173], v[30:33]
	v_mfma_f32_16x16x32_bf16 v[6:9], v[154:157], v[170:173], v[6:9]
	v_mfma_f32_16x16x32_bf16 v[26:29], v[146:149], v[190:193], v[26:29]
	v_mfma_f32_16x16x32_bf16 v[2:5], v[154:157], v[190:193], v[2:5]
	v_mfma_f32_16x16x32_bf16 v[74:77], v[146:149], v[198:201], v[74:77]
	v_mfma_f32_16x16x32_bf16 v[50:53], v[154:157], v[198:201], v[50:53]
	v_mfma_f32_16x16x32_bf16 v[34:37], v[150:153], v[166:169], v[34:37]
	v_mfma_f32_16x16x32_bf16 v[10:13], v[158:161], v[166:169], v[10:13]
	v_mfma_f32_16x16x32_bf16 v[30:33], v[150:153], v[174:177], v[30:33]
	v_mfma_f32_16x16x32_bf16 v[6:9], v[158:161], v[174:177], v[6:9]
	v_mfma_f32_16x16x32_bf16 v[26:29], v[150:153], v[194:197], v[26:29]
	v_mfma_f32_16x16x32_bf16 v[2:5], v[158:161], v[194:197], v[2:5]
	v_mfma_f32_16x16x32_bf16 v[74:77], v[150:153], v[202:205], v[74:77]
	v_mfma_f32_16x16x32_bf16 v[50:53], v[158:161], v[202:205], v[50:53]
	s_setprio 0
	s_barrier
	s_add_i32 vcc_lo, vcc_lo, 2
	s_add_u32 s12, s12, 0x100
	s_addc_u32 s13, s13, 0
	s_add_u32 s37, s37, 0x100
	s_addc_u32 s41, s41, 0
	s_cmp_gt_u32 vcc_lo, 29
	s_cbranch_scc0 .LBB0_1783
	s_and_b64 vcc, exec, s[24:25]
	s_cbranch_vccz .LBB0_1786
	s_barrier
